# A2 pass: first two tile DMAs issued inside the unit prologue (in place of the old tile-0 staging), hidden behind the Q norm work
# speedup vs baseline: 1.0030x; 1.0030x over previous
; __device__ __forceinline__ float bf2f(unsigned short b) { return __uint_as_float((unsigned)b << 16); }
; __device__ __forceinline__ float sum_x32(float v) { auto rr = __builtin_amdgcn_permlane32_swap(__float_as_uint(v), __float_as_uint(v), false, false); return __uint_as_float(rr[0]) + __uint_as_float(rr[1]); }
; __device__ __forceinline__ void attn_pass_A2(const int tid, unsigned char* smem, const bf16_t* Q0w, int qpitch, const bf16_t* Kb, int kpitch, const bf16_t* Vb, int vpitch,
;                                              int b, int ntiles, float kmax, f32x16 (&o)[2][2], float (&linv)[2]) {
;     ...
;     const int lane = tid & 63, r32 = lane & 31, hi = lane >> 5;
;     float nshift[2], lsum[2] = {0.f, 0.f};
;     unsigned char* qs = smem + 2 * BUF + ((tid >> 6) * 64 + r32) * KP + hi * 16;
; #pragma unroll
;     for (int qb = 0; qb < 2; ++qb) {
;         const bf16_t* qp = Q0w + (size_t)(32 * qb + r32) * qpitch + 8 * hi; float ssq = 0.f;
; #pragma unroll
;         for (int ds = 0; ds < 4; ++ds) { const bf16x8 qv = *(const bf16x8*)(qp + 16 * ds); *(bf16x8*)(qs + qb * 32 * KP + ds * 32) = qv;
; #pragma unroll
;             for (int j = 0; j < 8; ++j) { const float f = bf2f((unsigned short)qv[j]); ssq += f * f; } }
;         nshift[qb] = -sqrtf(sum_x32(ssq)) * kmax;
; #pragma unroll
;         for (int d0 = 0; d0 < 2; ++d0)
; #pragma unroll
;             for (int r = 0; r < 16; ++r) o[qb][d0][r] = 0.f;
;     }
; __device__ __forceinline__ void attn_unit_A2(const Frame& F, const Params& P, int l, int b, int h, size_t qrow0, int nq, int ntiles, float kmax, size_t ooff) {
;     ...
;     { const int wrow = (F.wave * 64 < nq) ? F.wave * 64 : (F.wave - 4) * 64;
;       attn_pass_A2(F.tid, F.lds, YAB + (qrow0 + wrow) * 1024 + 64 * h, 1024, KA + 64 * (h >> 2), 128, VA + 64 * (h >> 2), 128, b, ntiles, kmax, o, linv); }
.LBB0_417:
	s_and_b64 vcc, exec, s[0:1]
	s_cbranch_vccz .LBB0_394
	s_and_b32 s0, s27, 0xffffffc0
	s_add_i32 s1, s0, 0xffffff00
	s_cmp_lt_i32 s0, s11
	s_cselect_b32 s0, s0, s1
	s_ashr_i32 s1, s0, 31
	s_add_u32 s0, s8, s0
	s_addc_u32 s1, s9, s1
	s_lshl_b64 s[0:1], s[0:1], 11
	v_readlane_b32 s2, v253, 22
	v_readlane_b32 s3, v253, 23
	s_add_u32 s2, s2, s0
	s_addc_u32 s3, s3, s1
	s_lshl_b32 s0, s26, 6
	s_ashr_i32 s1, s0, 31
	s_lshl_b64 s[12:13], s[0:1], 1
	s_add_u32 s0, s2, s12
	s_addc_u32 s1, s3, s13
	v_mov_b32_e32 v139, v193
	v_lshl_add_u64 v[0:1], s[0:1], 0, v[138:139]
	v_lshlrev_b32_e32 v192, 11, v218
	v_lshl_add_u64 v[0:1], v[0:1], 0, v[192:193]
	global_load_dwordx4 v[20:23], v[0:1], off
	global_load_dwordx4 v[24:27], v[0:1], off offset:32
	global_load_dwordx4 v[28:31], v[0:1], off offset:64
	global_load_dwordx4 v[32:35], v[0:1], off offset:96
	s_mov_b32 s0, 0x10000
	v_add_co_u32_e32 v10, vcc, s0, v0
	s_movk_i32 s0, 0x90
	s_nop 0
	v_addc_co_u32_e32 v11, vcc, 0, v1, vcc
	global_load_dwordx4 v[16:19], v[10:11], off
	v_and_b32_e32 v1, 0xfffffdf, v197
	v_mul_lo_u32 v1, v1, s0
	v_add_u32_e32 v1, 0, v1
	v_add_u32_e32 v139, v1, v138
	global_load_dwordx4 v[2:5], v[10:11], off offset:32
	global_load_dwordx4 v[6:9], v[10:11], off offset:64
	s_nop 0
	global_load_dwordx4 v[10:13], v[10:11], off offset:96
	s_lshl_b32 s0, s26, 4
	s_andn2_b32 s0, s0, 63
	s_ashr_i32 s1, s0, 31
	s_lshl_b64 s[0:1], s[0:1], 1
	v_readlane_b32 s2, v251, 33
	s_add_u32 s14, s2, s0
	v_readlane_b32 s2, v251, 34
	s_addc_u32 s15, s2, s1
	v_readlane_b32 s2, v251, 35
	s_add_u32 s16, s2, s0
	s_mov_b32 s2, 0xf800000
	v_readlane_b32 s0, v251, 36
	s_addc_u32 s17, s0, s1
	v_and_b32_e32 v192, 0x70, v217
	v_mov_b32_e32 v0, 0
	s_mov_b32 s3, 0
	v_lshl_add_u64 v[140:141], s[14:15], 0, v[192:193]
	v_lshl_add_u64 v[142:143], s[16:17], 0, v[192:193]
	v_mul_u32_u24_e32 v173, 0xc0, v215
	v_lshlrev_b32_e32 v174, 1, v216
	v_mov_b32_e32 v52, v0
	v_mov_b32_e32 v53, v0
	v_mov_b32_e32 v54, v0
	v_mov_b32_e32 v55, v0
	v_mov_b32_e32 v56, v0
	v_mov_b32_e32 v57, v0
	v_mov_b32_e32 v58, v0
	v_mov_b32_e32 v59, v0
	v_mov_b32_e32 v60, v0
	v_mov_b32_e32 v61, v0
	v_mov_b32_e32 v62, v0
	v_mov_b32_e32 v63, v0
	v_mov_b32_e32 v64, v0
	v_mov_b32_e32 v65, v0
	v_mov_b32_e32 v66, v0
	v_mov_b32_e32 v67, v0
	v_mov_b32_e32 v68, v0
	v_mov_b32_e32 v69, v0
	v_mov_b32_e32 v70, v0
	v_mov_b32_e32 v71, v0
	v_mov_b32_e32 v72, v0
	v_mov_b32_e32 v73, v0
	v_mov_b32_e32 v74, v0
	v_mov_b32_e32 v75, v0
	v_mov_b32_e32 v76, v0
	v_mov_b32_e32 v77, v0
	v_mov_b32_e32 v78, v0
	v_mov_b32_e32 v79, v0
	v_mov_b32_e32 v144, v0
	v_mov_b32_e32 v145, v0
	s_waitcnt vmcnt(7)
	v_and_b32_e32 v36, 0xffff0000, v20
	v_lshlrev_b32_e32 v1, 16, v20
	v_lshlrev_b32_e32 v37, 16, v21
	s_waitcnt vmcnt(4)
; __device__ __forceinline__ float bf2f(unsigned short b) { return __uint_as_float((unsigned)b << 16); }
; __device__ __forceinline__ float sum_x32(float v) { auto rr = __builtin_amdgcn_permlane32_swap(__float_as_uint(v), __float_as_uint(v), false, false); return __uint_as_float(rr[0]) + __uint_as_float(rr[1]); }
; __device__ __forceinline__ void attn_pass_A2(const int tid, unsigned char* smem, const bf16_t* Q0w, int qpitch, const bf16_t* Kb, int kpitch, const bf16_t* Vb, int vpitch,
;                                              int b, int ntiles, float kmax, f32x16 (&o)[2][2], float (&linv)[2]) {
;     ...
;         const bf16_t* qp = Q0w + (size_t)(32 * qb + r32) * qpitch + 8 * hi; float ssq = 0.f;
; #pragma unroll
;         for (int ds = 0; ds < 4; ++ds) { const bf16x8 qv = *(const bf16x8*)(qp + 16 * ds); *(bf16x8*)(qs + qb * 32 * KP + ds * 32) = qv;
; #pragma unroll
;             for (int j = 0; j < 8; ++j) { const float f = bf2f((unsigned short)qv[j]); ssq += f * f; } }
;         nshift[qb] = -sqrtf(sum_x32(ssq)) * kmax;
;     ...
;     const int krow = tid >> 3, kch = tid & 7;
;     u32x4 kreg, vreg;
;     auto gload = [&](int kt) {
;         const size_t rb = kt < 4 ? (size_t)(NLAT + 256 * b + 64 * kt) : (size_t)(SEQ * b + 64 * (kt - 4));
;         kreg = *(const u32x4*)(Kb + (rb + krow) * kpitch + 8 * kch); vreg = *(const u32x4*)(Vb + (rb + krow) * vpitch + 8 * kch);
;     };
;     auto lwrite = [&](int buf) { unsigned char* Ks = smem + buf * BUF; *(u32x4*)(Ks + krow * KP + 16 * kch) = kreg; *(u32x4*)(Ks + KBYTES + krow * VP + 16 * kch) = vreg; };
;     gload(0); lwrite(0); __syncthreads();
	ds_write_b128 v139, v[32:35] offset:43104
	v_and_b32_e32 v15, 0xffff0000, v34
	v_lshlrev_b32_e32 v14, 16, v34
	v_mul_f32_e32 v34, v36, v36
	v_fmac_f32_e32 v34, v1, v1
	v_and_b32_e32 v38, 0xffff0000, v21
	v_fmac_f32_e32 v34, v37, v37
	v_lshlrev_b32_e32 v39, 16, v22
	v_fmac_f32_e32 v34, v38, v38
	ds_write_b128 v139, v[20:23] offset:43008
	v_and_b32_e32 v22, 0xffff0000, v22
	v_fmac_f32_e32 v34, v39, v39
	v_lshlrev_b32_e32 v40, 16, v23
	v_fmac_f32_e32 v34, v22, v22
	v_and_b32_e32 v23, 0xffff0000, v23
	v_fmac_f32_e32 v34, v40, v40
	v_lshlrev_b32_e32 v41, 16, v24
	v_fmac_f32_e32 v34, v23, v23
	ds_write_b128 v139, v[24:27] offset:43040
	v_and_b32_e32 v24, 0xffff0000, v24
	v_fmac_f32_e32 v34, v41, v41
	v_lshlrev_b32_e32 v42, 16, v25
	v_fmac_f32_e32 v34, v24, v24
	v_and_b32_e32 v25, 0xffff0000, v25
	v_fmac_f32_e32 v34, v42, v42
	v_lshlrev_b32_e32 v43, 16, v26
	v_fmac_f32_e32 v34, v25, v25
	v_and_b32_e32 v26, 0xffff0000, v26
	v_fmac_f32_e32 v34, v43, v43
	v_lshlrev_b32_e32 v44, 16, v27
	v_fmac_f32_e32 v34, v26, v26
	v_and_b32_e32 v27, 0xffff0000, v27
	v_fmac_f32_e32 v34, v44, v44
	v_lshlrev_b32_e32 v45, 16, v28
	v_fmac_f32_e32 v34, v27, v27
	ds_write_b128 v139, v[28:31] offset:43072
	v_and_b32_e32 v28, 0xffff0000, v28
	v_fmac_f32_e32 v34, v45, v45
	v_lshlrev_b32_e32 v46, 16, v29
	v_fmac_f32_e32 v34, v28, v28
	v_and_b32_e32 v29, 0xffff0000, v29
	v_fmac_f32_e32 v34, v46, v46
	v_lshlrev_b32_e32 v47, 16, v30
	v_fmac_f32_e32 v34, v29, v29
	v_and_b32_e32 v30, 0xffff0000, v30
	v_fmac_f32_e32 v34, v47, v47
	v_lshlrev_b32_e32 v48, 16, v31
	v_fmac_f32_e32 v34, v30, v30
	v_and_b32_e32 v31, 0xffff0000, v31
	v_fmac_f32_e32 v34, v48, v48
	v_lshlrev_b32_e32 v49, 16, v32
	v_fmac_f32_e32 v34, v31, v31
	v_and_b32_e32 v32, 0xffff0000, v32
	v_fmac_f32_e32 v34, v49, v49
	v_lshlrev_b32_e32 v50, 16, v33
	v_fmac_f32_e32 v34, v32, v32
	v_and_b32_e32 v33, 0xffff0000, v33
	v_fmac_f32_e32 v34, v50, v50
	v_pk_mul_f32 v[14:15], v[14:15], v[14:15]
	v_fmac_f32_e32 v34, v33, v33
	v_and_b32_e32 v21, 0xffff0000, v35
	v_lshlrev_b32_e32 v20, 16, v35
	v_add_f32_e32 v14, v14, v34
	v_pk_mul_f32 v[20:21], v[20:21], v[20:21]
	v_add_f32_e32 v14, v15, v14
	v_add_f32_e32 v14, v20, v14
	v_add_f32_e32 v14, v21, v14
	v_mov_b32_e32 v15, v14
	s_nop 1
	v_permlane32_swap_b32_e32 v14, v15
	v_add_f32_e32 v14, v14, v15
	v_mul_f32_e32 v15, 0x4f800000, v14
	v_cmp_gt_f32_e32 vcc, s2, v14
	s_waitcnt vmcnt(3)
	ds_write_b128 v139, v[16:19] offset:47616
	v_lshlrev_b32_e32 v35, 16, v16
	v_cndmask_b32_e32 v14, v14, v15, vcc
	v_sqrt_f32_e32 v15, v14
	v_and_b32_e32 v16, 0xffff0000, v16
	v_mul_f32_e32 v1, v16, v16
	v_lshlrev_b32_e32 v36, 16, v17
	v_fmac_f32_e32 v1, v35, v35
	v_and_b32_e32 v17, 0xffff0000, v17
	v_fmac_f32_e32 v1, v36, v36
	v_add_u32_e32 v16, -1, v15
	v_fmac_f32_e32 v1, v17, v17
	v_add_u32_e32 v17, 1, v15
	v_fma_f32 v20, -v16, v15, v14
	v_fma_f32 v21, -v17, v15, v14
	v_cmp_ge_f32_e64 s[0:1], 0, v20
	v_lshlrev_b32_e32 v51, 16, v18
	v_fmac_f32_e32 v1, v51, v51
	v_cndmask_b32_e64 v15, v15, v16, s[0:1]
	v_cmp_lt_f32_e64 s[0:1], 0, v21
	v_mov_b32_e32 v32, v0
	v_mov_b32_e32 v33, v0
	v_cndmask_b32_e64 v15, v15, v17, s[0:1]
	v_mul_f32_e32 v16, 0x37800000, v15
	v_cndmask_b32_e32 v15, v15, v16, vcc
	v_cmp_class_f32_e32 vcc, v14, v227
	s_lshl_b32 s0, s10, 8
	s_add_i32 s0, s0, 0x8000
	v_cndmask_b32_e32 v14, v15, v14, vcc
	v_mul_f32_e64 v16, v214, -v14
	v_and_b32_e32 v14, 0xffff0000, v18
	v_fmac_f32_e32 v1, v14, v14
	v_lshlrev_b32_e32 v14, 16, v19
	s_ashr_i32 s1, s0, 31
	v_fmac_f32_e32 v1, v14, v14
	v_lshl_add_u64 v[14:15], s[0:1], 0, v[136:137]
	v_lshlrev_b64 v[14:15], 8, v[14:15]
	v_and_b32_e32 v17, 0xffff0000, v19
	v_lshl_add_u64 v[18:19], s[14:15], 0, v[14:15]
	v_lshl_add_u64 v[18:19], v[18:19], 0, v[192:193]
	v_lshl_add_u64 v[14:15], s[16:17], 0, v[14:15]
	s_mov_b64 s[66:67], s[14:15]
	s_mov_b64 s[68:69], s[16:17]
	s_lshl_b32 s70, s10, 8
	s_add_i32 s65, s70, 0x8000
	s_lshl_b32 s70, s10, 13
	s_add_i32 s32, s70, 0xffffff00
	s_lshr_b32 s56, s27, 6
	s_lshl_b32 s56, s56, 10
	v_and_b32_e32 v132, 7, v197
	v_bfe_u32 v133, v136, 1, 3
	v_xor_b32_e32 v133, v133, v132
	v_lshlrev_b32_e32 v133, 4, v133
	v_lshl_add_u32 v236, v136, 8, v133
	v_bfe_u32 v134, v136, 1, 1
	v_lshlrev_b32_e32 v134, 2, v134
	v_xor_b32_e32 v134, v134, v132
	v_lshlrev_b32_e32 v134, 4, v134
	v_lshl_add_u32 v234, v136, 8, v134
	s_add_i32 s70, s65, 0
	s_lshl_b32 s70, s70, 8
	s_add_u32 s60, s66, s70
	s_addc_u32 s61, s67, 0
	s_add_u32 s62, s68, s70
	s_addc_u32 s63, s69, 0
	s_mov_b32 m0, s56
	s_nop 0
	global_load_lds_dwordx4 v236, s[60:61]
	s_add_i32 m0, s56, 0x2000
	s_nop 0
	global_load_lds_dwordx4 v234, s[62:63]
	s_add_i32 s70, s65, 64
	s_lshl_b32 s70, s70, 8
	s_add_u32 s60, s66, s70
	s_addc_u32 s61, s67, 0
	s_add_u32 s62, s68, s70
	s_addc_u32 s63, s69, 0
	s_add_i32 m0, s56, 0x4000
	s_nop 0
	global_load_lds_dwordx4 v236, s[60:61]
	s_add_i32 m0, s56, 0x6000
	s_nop 0
	global_load_lds_dwordx4 v234, s[62:63]
	v_lshl_add_u64 v[14:15], v[14:15], 0, v[192:193]

; __device__ __forceinline__ float bf2f(unsigned short b) { return __uint_as_float((unsigned)b << 16); }
; __device__ __forceinline__ float sum_x32(float v) { auto rr = __builtin_amdgcn_permlane32_swap(__float_as_uint(v), __float_as_uint(v), false, false); return __uint_as_float(rr[0]) + __uint_as_float(rr[1]); }
; __device__ __forceinline__ void attn_pass_A2(const int tid, unsigned char* smem, const bf16_t* Q0w, int qpitch, const bf16_t* Kb, int kpitch, const bf16_t* Vb, int vpitch,
;                                              int b, int ntiles, float kmax, f32x16 (&o)[2][2], float (&linv)[2]) {
;     ...
;         const bf16_t* qp = Q0w + (size_t)(32 * qb + r32) * qpitch + 8 * hi; float ssq = 0.f;
; #pragma unroll
;         for (int ds = 0; ds < 4; ++ds) { const bf16x8 qv = *(const bf16x8*)(qp + 16 * ds); *(bf16x8*)(qs + qb * 32 * KP + ds * 32) = qv;
; #pragma unroll
;             for (int j = 0; j < 8; ++j) { const float f = bf2f((unsigned short)qv[j]); ssq += f * f; } }
;         nshift[qb] = -sqrtf(sum_x32(ssq)) * kmax;
	v_fmac_f32_e32 v1, v17, v17
	s_waitcnt vmcnt(6)
	v_lshlrev_b32_e32 v14, 16, v2
	v_fmac_f32_e32 v1, v14, v14
	v_and_b32_e32 v14, 0xffff0000, v2
	v_fmac_f32_e32 v1, v14, v14
	v_lshlrev_b32_e32 v14, 16, v3
	v_fmac_f32_e32 v1, v14, v14
	v_and_b32_e32 v14, 0xffff0000, v3
	v_fmac_f32_e32 v1, v14, v14
	v_lshlrev_b32_e32 v14, 16, v4
	v_fmac_f32_e32 v1, v14, v14
	v_and_b32_e32 v14, 0xffff0000, v4
	v_fmac_f32_e32 v1, v14, v14
	v_lshlrev_b32_e32 v14, 16, v5
	v_fmac_f32_e32 v1, v14, v14
	v_and_b32_e32 v14, 0xffff0000, v5
	v_fmac_f32_e32 v1, v14, v14
	s_waitcnt vmcnt(5)
	v_lshlrev_b32_e32 v14, 16, v6
	v_fmac_f32_e32 v1, v14, v14
	v_and_b32_e32 v14, 0xffff0000, v6
	v_fmac_f32_e32 v1, v14, v14
	v_lshlrev_b32_e32 v14, 16, v7
	v_fmac_f32_e32 v1, v14, v14
	v_and_b32_e32 v14, 0xffff0000, v7
	v_fmac_f32_e32 v1, v14, v14
	v_lshlrev_b32_e32 v14, 16, v8
	v_fmac_f32_e32 v1, v14, v14
	v_and_b32_e32 v14, 0xffff0000, v8
	v_fmac_f32_e32 v1, v14, v14
	v_lshlrev_b32_e32 v14, 16, v9
	v_fmac_f32_e32 v1, v14, v14
	v_and_b32_e32 v14, 0xffff0000, v9
	v_fmac_f32_e32 v1, v14, v14
	s_waitcnt vmcnt(4)
	v_lshlrev_b32_e32 v14, 16, v10
	v_fmac_f32_e32 v1, v14, v14
	v_and_b32_e32 v14, 0xffff0000, v10
	v_fmac_f32_e32 v1, v14, v14
	v_lshlrev_b32_e32 v14, 16, v11
	v_fmac_f32_e32 v1, v14, v14
	v_and_b32_e32 v14, 0xffff0000, v11
	v_fmac_f32_e32 v1, v14, v14
	v_and_b32_e32 v15, 0xffff0000, v12
	v_lshlrev_b32_e32 v14, 16, v12
	v_pk_mul_f32 v[14:15], v[14:15], v[14:15]
	ds_write_b128 v139, v[2:5] offset:47648
	ds_write_b128 v139, v[6:9] offset:47680
	ds_write_b128 v139, v[10:13] offset:47712
	v_add_f32_e32 v1, v14, v1
	v_add_f32_e32 v1, v15, v1
	v_and_b32_e32 v15, 0xffff0000, v13
	v_lshlrev_b32_e32 v14, 16, v13
	v_pk_mul_f32 v[14:15], v[14:15], v[14:15]
	v_mov_b32_e32 v17, v16
	v_add_f32_e32 v1, v14, v1
	v_add_f32_e32 v1, v15, v1
	v_mov_b32_e32 v14, v1
	s_nop 1
	v_permlane32_swap_b32_e32 v1, v14
	v_add_f32_e32 v1, v1, v14
	v_mul_f32_e32 v14, 0x4f800000, v1
	v_cmp_gt_f32_e32 vcc, s2, v1
	v_mov_b32_e32 v18, v16
	v_mov_b32_e32 v19, v16
	v_cndmask_b32_e32 v1, v1, v14, vcc
	v_sqrt_f32_e32 v14, v1
	v_mov_b32_e32 v20, v16
	v_mov_b32_e32 v21, v16
	v_mov_b32_e32 v22, v16
	v_add_u32_e32 v2, -1, v14
	v_fma_f32 v3, -v2, v14, v1
	v_cmp_ge_f32_e64 s[0:1], 0, v3
	v_add_u32_e32 v3, 1, v14
	v_fma_f32 v4, -v3, v14, v1
	v_cndmask_b32_e64 v2, v14, v2, s[0:1]
	v_cmp_lt_f32_e64 s[0:1], 0, v4
	v_mov_b32_e32 v23, v16
	v_mov_b32_e32 v24, v16
	v_cndmask_b32_e64 v2, v2, v3, s[0:1]
	v_mul_f32_e32 v3, 0x37800000, v2
	v_cndmask_b32_e32 v2, v2, v3, vcc
	v_cmp_class_f32_e32 vcc, v1, v227
	s_movk_i32 s0, 0xc0
	v_mul_lo_u32 v172, v136, s0
	v_cndmask_b32_e32 v1, v2, v1, vcc
	v_add3_u32 v2, 0, v212, v192
	v_mul_f32_e64 v80, v214, -v1

; __device__ __forceinline__ void attn_pass_A2(const int tid, unsigned char* smem, const bf16_t* Q0w, int qpitch, const bf16_t* Kb, int kpitch, const bf16_t* Vb, int vpitch,
;                                              int b, int ntiles, float kmax, f32x16 (&o)[2][2], float (&linv)[2]) {
;     ...
;     auto lwrite = [&](int buf) { unsigned char* Ks = smem + buf * BUF; *(u32x4*)(Ks + krow * KP + 16 * kch) = kreg; *(u32x4*)(Ks + KBYTES + krow * VP + 16 * kch) = vreg; };
;     gload(0); lwrite(0); __syncthreads();
	v_mad_u64_u32 v[2:3], s[0:1], v136, 48, v[2:3]

; __device__ __forceinline__ void attn_pass_A2(const int tid, unsigned char* smem, const bf16_t* Q0w, int qpitch, const bf16_t* Kb, int kpitch, const bf16_t* Vb, int vpitch,
;                                              int b, int ntiles, float kmax, f32x16 (&o)[2][2], float (&linv)[2]) {
;     ...
; #pragma unroll
;         for (int d0 = 0; d0 < 2; ++d0)
; #pragma unroll
;             for (int r = 0; r < 16; ++r) o[qb][d0][r] = 0.f;
;     }
;     const int krow = tid >> 3, kch = tid & 7;
;     u32x4 kreg, vreg;
;     auto gload = [&](int kt) {
;         const size_t rb = kt < 4 ? (size_t)(NLAT + 256 * b + 64 * kt) : (size_t)(SEQ * b + 64 * (kt - 4));
;         kreg = *(const u32x4*)(Kb + (rb + krow) * kpitch + 8 * kch); vreg = *(const u32x4*)(Vb + (rb + krow) * vpitch + 8 * kch);
;     };
;     auto lwrite = [&](int buf) { unsigned char* Ks = smem + buf * BUF; *(u32x4*)(Ks + krow * KP + 16 * kch) = kreg; *(u32x4*)(Ks + KBYTES + krow * VP + 16 * kch) = vreg; };
;     gload(0); lwrite(0); __syncthreads();
;     const int nhalf = (lane >> 4) & 1, q4 = (lane & 15) >> 2, p4 = lane & 3;
;     for (int kt = 0; kt < ntiles; ++kt) {
;         if (kt + 1 < ntiles) gload(kt + 1);
;         const unsigned char* Ks = smem + (kt & 1) * BUF; const unsigned char* Vs = Ks + KBYTES;
;         const unsigned char* kp = Ks + r32 * KP + hi * 16;
;         const unsigned char* vp = Vs + (4 * hi + q4) * VP + (16 * nhalf + 4 * p4) * 2;
; #pragma unroll
;         for (int kb = 0; kb < 2; ++kb) {
;             bf16x8 pf[2][2];
;             {
;                 f32x16 s0, s1;
; #pragma unroll
;                 for (int r = 0; r < 16; ++r) { s0[r] = nshift[0]; s1[r] = nshift[1]; }
; #pragma unroll
;                 for (int ds = 0; ds < 4; ++ds) {
;                     const bf16x8 kf = *(const bf16x8*)(kp + kb * 32 * KP + ds * 32);
;                     const bf16x8 q0 = *(const bf16x8*)(qs + ds * 32), q1 = *(const bf16x8*)(qs + 32 * KP + ds * 32);
;                     s0 = __builtin_amdgcn_mfma_f32_32x32x16_bf16(kf, q0, s0, 0, 0, 0);
;                     s1 = __builtin_amdgcn_mfma_f32_32x32x16_bf16(kf, q1, s1, 0, 0, 0);
;                 }
;                 float l0 = 0.f, l1 = 0.f;
; #pragma unroll
;                 for (int r = 0; r < 16; ++r) { s0[r] = __builtin_amdgcn_exp2f(s0[r]); l0 += s0[r]; }
; #pragma unroll
	v_mov_b32_e32 v25, v16
	v_mov_b32_e32 v26, v16
	v_mov_b32_e32 v27, v16
	v_mov_b32_e32 v28, v16
	v_mov_b32_e32 v29, v16
	v_mov_b32_e32 v30, v16
	v_mov_b32_e32 v31, v16
	v_mov_b32_e32 v81, v80
	v_mov_b32_e32 v82, v80
	v_mov_b32_e32 v83, v80
	v_mov_b32_e32 v84, v80
	v_mov_b32_e32 v85, v80
	v_mov_b32_e32 v86, v80
	v_mov_b32_e32 v87, v80
	v_mov_b32_e32 v88, v80
	v_mov_b32_e32 v89, v80
	v_mov_b32_e32 v90, v80
	v_mov_b32_e32 v91, v80
	v_mov_b32_e32 v92, v80
	v_mov_b32_e32 v93, v80
	v_mov_b32_e32 v94, v80
	v_mov_b32_e32 v95, v80
	s_mov_b32 s2, 64
	v_mov_b32_e32 v1, v0
	v_mov_b32_e32 v2, v0
	v_mov_b32_e32 v3, v0
	v_mov_b32_e32 v4, v0
	v_mov_b32_e32 v5, v0
	v_mov_b32_e32 v6, v0
	v_mov_b32_e32 v7, v0
	v_mov_b32_e32 v8, v0
	v_mov_b32_e32 v9, v0
	v_mov_b32_e32 v10, v0
	v_mov_b32_e32 v11, v0
	v_mov_b32_e32 v12, v0
	v_mov_b32_e32 v13, v0
	v_mov_b32_e32 v14, v0
	v_mov_b32_e32 v15, v0
	v_mov_b32_e32 v34, v0
	v_mov_b32_e32 v35, v0
	v_mov_b32_e32 v36, v0
	v_mov_b32_e32 v37, v0
	v_mov_b32_e32 v38, v0
	v_mov_b32_e32 v39, v0
	v_mov_b32_e32 v40, v0
	v_mov_b32_e32 v41, v0
	v_mov_b32_e32 v42, v0
	v_mov_b32_e32 v43, v0
	v_mov_b32_e32 v44, v0
	v_mov_b32_e32 v45, v0
	v_mov_b32_e32 v46, v0
	v_mov_b32_e32 v47, v0
	v_mov_b32_e32 v48, v0
	v_mov_b32_e32 v49, v0
	v_mov_b32_e32 v50, v0
	v_mov_b32_e32 v51, v0
	s_waitcnt vmcnt(0) lgkmcnt(0)
	s_barrier
	s_mov_b32 s59, 0
	v_min_f32_e32 v16, v16, v80
	v_mov_b32_e32 v17, v16
	v_mov_b32_e32 v18, v16
	v_mov_b32_e32 v19, v16
	v_mov_b32_e32 v20, v16
	v_mov_b32_e32 v21, v16
	v_mov_b32_e32 v22, v16
	v_mov_b32_e32 v23, v16
	v_mov_b32_e32 v24, v16
	v_mov_b32_e32 v25, v16
	v_mov_b32_e32 v26, v16
	v_mov_b32_e32 v27, v16
	v_mov_b32_e32 v28, v16
	v_mov_b32_e32 v29, v16
	v_mov_b32_e32 v30, v16
	v_mov_b32_e32 v31, v16
	ds_read_b128 v[146:149], v139 offset:43008
	ds_read_b128 v[150:153], v139 offset:43040
	ds_read_b128 v[154:157], v139 offset:43072
	ds_read_b128 v[158:161], v139 offset:43104
	ds_read_b128 v[176:179], v139 offset:47616
	ds_read_b128 v[180:183], v139 offset:47648
	ds_read_b128 v[184:187], v139 offset:47680
	ds_read_b128 v[188:191], v139 offset:47712
	v_bfe_u32 v132, v218, 1, 3
	v_lshrrev_b32_e32 v133, 4, v138
	v_xor_b32_e32 v132, v132, v133
	v_xor_b32_e32 v133, 0, v132
	v_lshlrev_b32_e32 v133, 4, v133
	v_lshl_or_b32 v170, v218, 7, v133
	v_xor_b32_e32 v133, 2, v132
	v_lshlrev_b32_e32 v133, 4, v133
	v_lshl_or_b32 v171, v218, 7, v133
	v_xor_b32_e32 v133, 4, v132
	v_lshlrev_b32_e32 v133, 4, v133
	v_lshl_or_b32 v210, v218, 7, v133
	v_xor_b32_e32 v133, 6, v132
	v_lshlrev_b32_e32 v133, 4, v133
	v_lshl_or_b32 v222, v218, 7, v133
	v_bfe_u32 v134, v215, 1, 1
	v_xor_b32_e32 v135, 0, v134
	v_lshl_add_u32 v135, v135, 6, v174
	v_lshl_add_u32 v223, v215, 7, v135
	v_xor_b32_e32 v135, 1, v134
	v_lshl_add_u32 v135, v135, 6, v174
	v_lshl_add_u32 v224, v215, 7, v135
	s_waitcnt vmcnt(0) lgkmcnt(0)
	s_barrier
	s_add_i32 s70, s59, 2
	s_cmp_lt_u32 s70, 4
	s_cselect_b32 s2, s65, s32
	s_lshl_b32 s3, s70, 6
	s_add_i32 s2, s2, s3
	s_lshl_b32 s2, s2, 8
	s_add_u32 s60, s66, s2
	s_addc_u32 s61, s67, 0
	s_add_u32 s62, s68, s2
	s_addc_u32 s63, s69, 0
	s_add_i32 m0, s56, 0x8000
	s_nop 0
	global_load_lds_dwordx4 v236, s[60:61]
	s_add_i32 m0, s56, 0xa000
	s_nop 0
	global_load_lds_dwordx4 v234, s[62:63]
	ds_read_b128 v[198:201], v170
	ds_read_b128 v[202:205], v171
	ds_read_b128 v[206:209], v210
	ds_read_b128 v[128:131], v222
	s_waitcnt lgkmcnt(3)
	v_mfma_f32_32x32x16_bf16 v[80:95], v[198:201], v[146:149], v[16:31]
	s_waitcnt lgkmcnt(2)
	v_mfma_f32_32x32x16_bf16 v[80:95], v[202:205], v[150:153], v[80:95]
	s_waitcnt lgkmcnt(1)
	v_mfma_f32_32x32x16_bf16 v[80:95], v[206:209], v[154:157], v[80:95]
	s_waitcnt lgkmcnt(0)
	v_mfma_f32_32x32x16_bf16 v[80:95], v[128:131], v[158:161], v[80:95]
	s_nop 7
	s_nop 3
	v_mfma_f32_32x32x16_bf16 v[96:111], v[198:201], v[176:179], v[16:31]
	ds_read_b128 v[198:201], v170 offset:4096
	v_exp_f32_e32 v80, v80
	v_exp_f32_e32 v81, v81
	v_exp_f32_e32 v82, v82
	v_add_f32_e32 v144, v144, v80
	v_exp_f32_e32 v83, v83
	v_add_f32_e32 v144, v144, v81
	v_cvt_pk_bf16_f32 v112, v80, v81
	v_exp_f32_e32 v84, v84
	v_add_f32_e32 v144, v144, v82
	v_exp_f32_e32 v85, v85
	v_add_f32_e32 v144, v144, v83
	v_cvt_pk_bf16_f32 v113, v82, v83
	v_exp_f32_e32 v86, v86
	v_mfma_f32_32x32x16_bf16 v[96:111], v[202:205], v[180:183], v[96:111]
	ds_read_b128 v[202:205], v171 offset:4096
	v_add_f32_e32 v144, v144, v84
	v_exp_f32_e32 v87, v87
	v_add_f32_e32 v144, v144, v85
	v_cvt_pk_bf16_f32 v114, v84, v85
	v_exp_f32_e32 v88, v88
	v_add_f32_e32 v144, v144, v86
	v_exp_f32_e32 v89, v89
	v_add_f32_e32 v144, v144, v87
	v_cvt_pk_bf16_f32 v115, v86, v87
	v_exp_f32_e32 v90, v90
	v_add_f32_e32 v144, v144, v88
	v_exp_f32_e32 v91, v91
	v_add_f32_e32 v144, v144, v89
	v_mfma_f32_32x32x16_bf16 v[96:111], v[206:209], v[184:187], v[96:111]
	ds_read_b128 v[206:209], v210 offset:4096
	v_cvt_pk_bf16_f32 v116, v88, v89
	v_exp_f32_e32 v92, v92
	v_add_f32_e32 v144, v144, v90
	v_exp_f32_e32 v93, v93
	v_add_f32_e32 v144, v144, v91
	v_cvt_pk_bf16_f32 v117, v90, v91
	v_exp_f32_e32 v94, v94
	v_add_f32_e32 v144, v144, v92
	v_exp_f32_e32 v95, v95
	v_add_f32_e32 v144, v144, v93
	v_cvt_pk_bf16_f32 v118, v92, v93
	v_add_f32_e32 v144, v144, v94
	v_add_f32_e32 v144, v144, v95
	v_cvt_pk_bf16_f32 v119, v94, v95
	v_mfma_f32_32x32x16_bf16 v[96:111], v[128:131], v[188:191], v[96:111]
	ds_read_b128 v[128:131], v222 offset:4096
	ds_read_b64_tr_b16 v[162:163], v223 offset:8192
	ds_read_b64_tr_b16 v[164:165], v223 offset:9216
	ds_read_b64_tr_b16 v[166:167], v224 offset:8192
	ds_read_b64_tr_b16 v[168:169], v224 offset:9216
	ds_read_b64_tr_b16 v[214:215], v223 offset:10240
	ds_read_b64_tr_b16 v[216:217], v223 offset:11264
	ds_read_b64_tr_b16 v[218:219], v224 offset:10240
	ds_read_b64_tr_b16 v[220:221], v224 offset:11264
	s_waitcnt lgkmcnt(8)
	s_nop 3
	s_add_i32 s71, s25, -7
	s_cmp_lt_i32 s59, s71
	s_cbranch_scc0 .Laattn_tail
